# sc1 partner-slot loads replace acquire fence in residual-rmsnorm epilogue; LDS-DMA staging rebalanced 4/4 per load segment; first two MFMAs of each compute segment hoisted above its barrier
# speedup vs baseline: 1.0123x; 1.0123x over previous
; #define PG8_STAGE(bufoff, gbase, voff) do { _Pragma("unroll") for (int _i = 0; _i < 2; ++_i) \
;         __builtin_amdgcn_global_load_lds((const unsigned*)((const char*)(gbase) + (voff)[_i]), (PG8_LAS unsigned*)(lds + (bufoff) + ldsw + _i * 8192), 16, 0, 0); } while (0)
; #define PG8_WAIT_V(n) asm volatile("s_waitcnt vmcnt(" #n ")" ::: "memory")
; #define PG8_BAR __builtin_amdgcn_s_barrier()
; template <class Epi, class Sched, bool ALIGN_EPI = false>
; __device__ __forceinline__ void gemm_phase(PG8_LAS unsigned char* lds, const Gemm g, const Sched& S, const Epi& E, int tid_in) {
;     ...
;     const int tid = tid_, wid = __builtin_amdgcn_readfirstlane(tid >> 6), lane = tid & 63, wr = wid >> 2, wc = wid & 3, fr = lane & 15, fq = lane >> 4;
;     const int lda = g.lda, ldb = g.ldb, nt = g.K / BK;
;     unsigned voffA[2], voffB[2];
; #pragma unroll
;     for (int i = 0; i < 2; ++i) { int R, C; stage_rc(tid * 16 + i * 8192, R, C); const int Rb = E.perm() ? ((R & ~31) + perm32(R & 31)) : R;
;         voffA[i] = (unsigned)(R * lda + C) * 2u; voffB[i] = (unsigned)(Rb * ldb + C) * 2u; }
;     const size_t kstep = (size_t)(BK * 2);
;     const size_t hstepA = (size_t)HALF * lda * 2, hstepB = (size_t)HALF * ldb * 2;
;     const size_t tstepA = 2 * hstepA, tstepB = 2 * hstepB;
;     const unsigned ldsw = (unsigned)wid * 1024u;
;     const int aoff = lds_byte(wr * 64 + fr, fq * 8), boff = lds_byte(wc * 32 + fr, fq * 8);
;     ...
;     PG8_STAGE(PG8_SB(0, 0), cB, voffB); PG8_STAGE(PG8_SB(0, 1), cB + hstepB, voffB); PG8_STAGE(PG8_SA(0, 0), cA, voffA); PG8_STAGE(PG8_SA(0, 1), cA + hstepA, voffA);
;     if (wr == 1) PG8_BAR;
;     PG8_WAIT_V(2); PG8_BAR;
;     PG8_STAGE(PG8_SB(1, 0), cB + kstep, voffB); PG8_STAGE(PG8_SA(1, 0), cA + kstep, voffA); PG8_STAGE(PG8_SB(1, 1), cB + hstepB + kstep, voffB);
;     PG8_WAIT_V(6); PG8_BAR;
.LBB0_254:
	s_add_i32 m0, s70, 0x18000
	v_lshl_add_u64 v[130:131], v[130:131], 0, s[96:97]
	s_waitcnt vmcnt(2)
	s_barrier
	global_load_lds_dwordx4 v[130:131], off
	v_lshl_add_u64 v[130:131], v[132:133], 0, s[96:97]
	s_add_i32 m0, s70, 0x1a000
	s_add_i32 s74, s70, 0x8000
	global_load_lds_dwordx4 v[130:131], off
	v_lshl_add_u64 v[130:131], v[138:139], 0, s[96:97]
	s_add_i32 s75, s70, 0xa000
	v_or_b32_e32 v244, s66, v243
	s_add_i32 m0, s70, 0x1c000
	v_lshl_add_u64 v[130:131], v[134:135], 0, s[96:97]
	global_load_lds_dwordx4 v[130:131], off
	v_lshl_add_u64 v[130:131], v[136:137], 0, s[96:97]
	s_add_i32 m0, s70, 0x1e000
	v_lshlrev_b32_e32 v80, 4, v143
	global_load_lds_dwordx4 v[130:131], off
	v_lshlrev_b32_e32 v130, 6, v244
	v_lshlrev_b32_e32 v131, 2, v244
	s_lshr_b32 s76, s16, 6
	v_and_or_b32 v130, v130, s77, v80
	s_lshl_b32 s14, s21, 13
	v_and_b32_e32 v131, 32, v131
	v_bitop3_b32 v130, v130, s14, v131 bitop3:0xde
	s_lshl_b32 s14, s34, 12
	v_lshlrev_b32_e32 v132, 2, v243
	s_add_i32 s77, s76, -2
	v_lshl_or_b32 v131, v243, 6, v80
	v_and_b32_e32 v132, 32, v132
	s_cmpk_lt_u32 s17, 0x100
	v_bitop3_b32 v245, v131, s14, v132 bitop3:0xde
	s_cselect_b64 s[14:15], -1, 0
	s_or_b32 s16, s34, s21
	s_cmp_eq_u32 s16, 0
	v_readlane_b32 s20, v253, 60
	s_cselect_b64 s[16:17], -1, 0
	s_sub_i32 s82, s19, s65
	v_readlane_b32 s22, v253, 62
	v_readlane_b32 s23, v253, 63
	s_lshl_b32 s79, s19, 2
	s_lshl_b32 s81, s19, 3
	s_lshl_b32 s83, s82, 4
	s_mov_b64 s[54:55], s[22:23]
	v_readlane_b32 s21, v253, 61
	s_add_u32 s20, s54, 0x8400600
	s_addc_u32 s21, s55, 0
	s_mul_i32 s91, s19, 12
	s_bitcmp0_b32 s18, 0
	s_mov_b32 s19, 0x13400000
	s_cselect_b32 s19, s19, 0x4400000
	s_add_u32 s26, s54, s19
	s_addc_u32 s27, s55, 0
	s_add_u32 s28, s54, 0x1fa00000
	s_addc_u32 s29, s55, 0
	s_lshl_b32 s19, s18, 11
	s_and_b32 s22, s19, 0xffffe000
	s_ashr_i32 s23, s22, 31
	s_lshl_b64 s[22:23], s[22:23], 2
	s_add_u32 s19, s54, s22
	s_addc_u32 s22, s55, s23
	s_add_u32 s84, s19, 0x10000
	s_addc_u32 s85, s22, 0
	s_and_b32 s19, s18, 2
	s_cmp_eq_u32 s19, 0
	s_cselect_b64 s[30:31], -1, 0
	s_cmp_lg_u32 s19, 0
	s_cselect_b64 s[36:37], -1, 0
	s_add_u32 s50, s54, 0x13400000
	v_lshl_add_u64 v[192:193], s[28:29], 0, v[80:81]
	s_addc_u32 s51, s55, 0
	v_add_u32_e32 v80, v146, v144
	v_or_b32_e32 v131, v143, v243
	s_add_u32 s52, s54, 0x1a500000
	v_add_lshl_u32 v80, v80, v145, 1
	s_waitcnt vmcnt(4)
	v_cmp_eq_u32_e64 s[44:45], 0, v131
	v_and_b32_e32 v131, 16, v142
	v_lshlrev_b32_e32 v132, 7, v143
	s_addc_u32 s53, s55, 0
	v_lshl_add_u64 v[194:195], s[0:1], 0, v[80:81]
	v_add_u32_e32 v80, v149, v147
	v_or3_b32 v131, v131, v132, s35
	s_cmp_lt_u32 s18, 4
	v_add_lshl_u32 v80, v80, v148, 1
	s_mov_b32 s78, 0
	v_cmp_eq_u32_e64 s[42:43], 0, v143
	v_or_b32_e32 v246, 0xfffff500, v131
	v_cmp_eq_u32_e64 s[46:47], 15, v243
	s_cselect_b64 s[54:55], -1, 0
	v_or_b32_e32 v247, s35, v142
	v_lshl_add_u64 v[196:197], s[0:1], 0, v[80:81]
	v_add_u32_e32 v248, 0, v130
	s_lshl_b32 s56, s34, 2
	s_barrier
	s_branch .LBB0_257

; #define PG8_STAGE(bufoff, gbase, voff) do { _Pragma("unroll") for (int _i = 0; _i < 2; ++_i) \
;         __builtin_amdgcn_global_load_lds((const unsigned*)((const char*)(gbase) + (voff)[_i]), (PG8_LAS unsigned*)(lds + (bufoff) + ldsw + _i * 8192), 16, 0, 0); } while (0)
; #define PG8_LDA(dst, b, h) do { _Pragma("unroll") for (int m = 0; m < 4; ++m) _Pragma("unroll") for (int k = 0; k < 2; ++k) dst[m][k] = *(const PG8_LAS bf16x8*)(lds + PG8_SA(b, h) + aoff + m * 2048 + k * 1024); } while (0)
; #define PG8_LDB(dst, b, h) do { _Pragma("unroll") for (int n = 0; n < 2; ++n) _Pragma("unroll") for (int k = 0; k < 2; ++k) dst[n][k] = *(const PG8_LAS bf16x8*)(lds + PG8_SB(b, h) + boff + n * 2048 + k * 1024); } while (0)
; #define PG8_MMA(ai, bj, At, Bt) do { __builtin_amdgcn_s_setprio(1); _Pragma("unroll") for (int m = 0; m < 4; ++m) _Pragma("unroll") for (int n = 0; n < 2; ++n) _Pragma("unroll") for (int k = 0; k < 2; ++k) \
;         acc[ai][bj][m][n] = __builtin_amdgcn_mfma_f32_16x16x32_bf16(Bt[n][k], At[m][k], acc[ai][bj][m][n], 0, 0, 0); __builtin_amdgcn_s_setprio(0); } while (0)
; #define PG8_WAIT_V(n) asm volatile("s_waitcnt vmcnt(" #n ")" ::: "memory")
; #define PG8_WAIT_L(n) asm volatile("s_waitcnt lgkmcnt(" #n ")" ::: "memory")
; #define PG8_BAR __builtin_amdgcn_s_barrier()
; #define PG8_SCHED __builtin_amdgcn_sched_barrier(0)
; template <class Epi, class Sched, bool ALIGN_EPI = false>
; __device__ __forceinline__ void gemm_phase(PG8_LAS unsigned char* lds, const Gemm g, const Sched& S, const Epi& E, int tid_in) {
;     ...
;             PG8_LDB(B0, 0, 0); PG8_LDB(B1, 0, 1); PG8_SCHED; PG8_LDA(At, 0, 0); PG8_STAGE(PG8_SA(1, 1), a1 + hstepA, voffA);
;             PG8_WAIT_V(8); PG8_WAIT_L(0); PG8_BAR; PG8_MMA(0, 0, At, B0); PG8_MMA(0, 1, At, B1); PG8_BAR; PG8_SCHED;
;             PG8_LDA(At, 0, 1); PG8_STAGE(PG8_SB(0, 0), b2, voffB); PG8_STAGE(PG8_SB(0, 1), b2 + hstepB, voffB); PG8_STAGE(PG8_SA(0, 0), a2, voffA);
;             PG8_WAIT_V(8); PG8_WAIT_L(0); PG8_BAR; PG8_MMA(1, 0, At, B0); PG8_MMA(1, 1, At, B1); PG8_BAR; PG8_SCHED;
.LBB0_267:
	s_add_i32 s63, s58, 2
	s_add_u32 s22, s60, 0x80
	s_addc_u32 s23, s61, 0
	s_add_i32 s89, 0, 0x10000
	s_cmp_eq_u32 s77, s58
	s_cselect_b32 s59, s19, s23
	s_cselect_b32 s58, s18, s22
	v_add_u32_e32 v80, s89, v245
	s_cselect_b32 s23, s35, s62
	s_cselect_b32 s22, s34, s57
	s_add_i32 s90, 0, 0x14000
	ds_read_b128 v[130:133], v80
	ds_read_b128 v[134:137], v80 offset:1024
	ds_read_b128 v[138:141], v80 offset:2048
	ds_read_b128 v[142:145], v80 offset:3072
	v_add_u32_e32 v80, s90, v245
	ds_read_b128 v[146:149], v80
	ds_read_b128 v[150:153], v80 offset:1024
	ds_read_b128 v[154:157], v80 offset:2048
	ds_read_b128 v[158:161], v80 offset:3072
	v_lshl_add_u64 v[210:211], s[60:61], 0, v[194:195]
	s_add_i32 m0, s70, 0xc000
	ds_read_b128 v[162:165], v248
	ds_read_b128 v[166:169], v248 offset:1024
	ds_read_b128 v[170:173], v248 offset:2048
	ds_read_b128 v[174:177], v248 offset:3072
	ds_read_b128 v[178:181], v248 offset:4096
	ds_read_b128 v[198:201], v248 offset:5120
	ds_read_b128 v[202:205], v248 offset:6144
	ds_read_b128 v[206:209], v248 offset:7168
	v_lshl_add_u64 v[212:213], s[60:61], 0, v[184:185]
	s_mov_b32 m0, s74
	v_lshl_add_u64 v[214:215], s[60:61], 0, v[188:189]
	global_load_lds_dwordx4 v[212:213], off
	s_mov_b32 m0, s75
	s_nop 0
	global_load_lds_dwordx4 v[214:215], off
	s_add_i32 m0, s70, 0xc000
	s_nop 0
	global_load_lds_dwordx4 v[210:211], off
	v_lshl_add_u64 v[210:211], s[60:61], 0, v[196:197]
	s_add_i32 m0, s70, 0xe000
	s_nop 0
	global_load_lds_dwordx4 v[210:211], off
	s_waitcnt vmcnt(8)
	s_waitcnt lgkmcnt(0)
	v_mfma_f32_16x16x32_bf16 v[4:7], v[130:133], v[162:165], v[4:7]
	v_mfma_f32_16x16x32_bf16 v[0:3], v[138:141], v[162:165], v[0:3]
	s_barrier
	s_setprio 1
	s_waitcnt lgkmcnt(0)
	v_mfma_f32_16x16x32_bf16 v[20:23], v[130:133], v[170:173], v[20:23]
	v_mfma_f32_16x16x32_bf16 v[16:19], v[138:141], v[170:173], v[16:19]
	v_mfma_f32_16x16x32_bf16 v[36:39], v[130:133], v[178:181], v[36:39]
	v_mfma_f32_16x16x32_bf16 v[32:35], v[138:141], v[178:181], v[32:35]
	v_mfma_f32_16x16x32_bf16 v[52:55], v[130:133], v[202:205], v[52:55]
	v_mfma_f32_16x16x32_bf16 v[48:51], v[138:141], v[202:205], v[48:51]
	v_mfma_f32_16x16x32_bf16 v[4:7], v[134:137], v[166:169], v[4:7]
	v_mfma_f32_16x16x32_bf16 v[0:3], v[142:145], v[166:169], v[0:3]
	v_mfma_f32_16x16x32_bf16 v[20:23], v[134:137], v[174:177], v[20:23]
	v_mfma_f32_16x16x32_bf16 v[16:19], v[142:145], v[174:177], v[16:19]
	v_mfma_f32_16x16x32_bf16 v[36:39], v[134:137], v[198:201], v[36:39]
	v_mfma_f32_16x16x32_bf16 v[32:35], v[142:145], v[198:201], v[32:35]
	v_mfma_f32_16x16x32_bf16 v[52:55], v[134:137], v[206:209], v[52:55]
	v_mfma_f32_16x16x32_bf16 v[48:51], v[142:145], v[206:209], v[48:51]
	s_setprio 0
	s_setprio 1
	v_mfma_f32_16x16x32_bf16 v[12:15], v[146:149], v[162:165], v[12:15]
	v_mfma_f32_16x16x32_bf16 v[8:11], v[154:157], v[162:165], v[8:11]
	v_mfma_f32_16x16x32_bf16 v[28:31], v[146:149], v[170:173], v[28:31]
	v_mfma_f32_16x16x32_bf16 v[24:27], v[154:157], v[170:173], v[24:27]
	v_mfma_f32_16x16x32_bf16 v[44:47], v[146:149], v[178:181], v[44:47]
	v_mfma_f32_16x16x32_bf16 v[40:43], v[154:157], v[178:181], v[40:43]
	v_mfma_f32_16x16x32_bf16 v[60:63], v[146:149], v[202:205], v[60:63]
	v_mfma_f32_16x16x32_bf16 v[56:59], v[154:157], v[202:205], v[56:59]
	v_mfma_f32_16x16x32_bf16 v[12:15], v[150:153], v[166:169], v[12:15]
	v_mfma_f32_16x16x32_bf16 v[8:11], v[158:161], v[166:169], v[8:11]
	v_mfma_f32_16x16x32_bf16 v[28:31], v[150:153], v[174:177], v[28:31]
	v_mfma_f32_16x16x32_bf16 v[24:27], v[158:161], v[174:177], v[24:27]
	v_mfma_f32_16x16x32_bf16 v[44:47], v[150:153], v[198:201], v[44:47]
	v_mfma_f32_16x16x32_bf16 v[40:43], v[158:161], v[198:201], v[40:43]
	v_mfma_f32_16x16x32_bf16 v[60:63], v[150:153], v[206:209], v[60:63]
	v_mfma_f32_16x16x32_bf16 v[56:59], v[158:161], v[206:209], v[56:59]
	s_setprio 0
	s_barrier
	s_add_i32 s89, s89, s69
	v_lshl_add_u64 v[210:211], s[22:23], 0, v[186:187]
	s_mov_b32 m0, s89
	ds_read_b128 v[162:165], v248 offset:16384
	ds_read_b128 v[166:169], v248 offset:17408
	ds_read_b128 v[170:173], v248 offset:18432
	ds_read_b128 v[174:177], v248 offset:19456
	ds_read_b128 v[178:181], v248 offset:20480
	ds_read_b128 v[198:201], v248 offset:21504
	ds_read_b128 v[202:205], v248 offset:22528
	ds_read_b128 v[206:209], v248 offset:23552
	global_load_lds_dwordx4 v[210:211], off
	s_add_i32 m0, s89, 0x2000
	v_lshl_add_u64 v[212:213], s[22:23], 0, v[190:191]
	s_add_u32 s22, s22, s33
	s_addc_u32 s23, s23, 0
	s_add_i32 s89, s90, s69
	global_load_lds_dwordx4 v[212:213], off
	v_lshl_add_u64 v[214:215], s[22:23], 0, v[186:187]
	s_mov_b32 m0, s89
	v_lshl_add_u64 v[216:217], s[22:23], 0, v[190:191]
	global_load_lds_dwordx4 v[214:215], off
	s_add_i32 m0, s89, 0x2000
	v_lshl_add_u64 v[218:219], s[58:59], 0, v[184:185]
	global_load_lds_dwordx4 v[216:217], off
	v_lshl_add_u64 v[228:229], s[58:59], 0, v[188:189]
	s_waitcnt vmcnt(6)
	s_waitcnt lgkmcnt(0)
	v_mfma_f32_16x16x32_bf16 v[64:67], v[130:133], v[162:165], v[64:67]
	v_mfma_f32_16x16x32_bf16 v[68:71], v[138:141], v[162:165], v[68:71]
	s_barrier
; #define PG8_STAGE(bufoff, gbase, voff) do { _Pragma("unroll") for (int _i = 0; _i < 2; ++_i) \
;         __builtin_amdgcn_global_load_lds((const unsigned*)((const char*)(gbase) + (voff)[_i]), (PG8_LAS unsigned*)(lds + (bufoff) + ldsw + _i * 8192), 16, 0, 0); } while (0)
; #define PG8_LDA(dst, b, h) do { _Pragma("unroll") for (int m = 0; m < 4; ++m) _Pragma("unroll") for (int k = 0; k < 2; ++k) dst[m][k] = *(const PG8_LAS bf16x8*)(lds + PG8_SA(b, h) + aoff + m * 2048 + k * 1024); } while (0)
; #define PG8_LDB(dst, b, h) do { _Pragma("unroll") for (int n = 0; n < 2; ++n) _Pragma("unroll") for (int k = 0; k < 2; ++k) dst[n][k] = *(const PG8_LAS bf16x8*)(lds + PG8_SB(b, h) + boff + n * 2048 + k * 1024); } while (0)
; #define PG8_MMA(ai, bj, At, Bt) do { __builtin_amdgcn_s_setprio(1); _Pragma("unroll") for (int m = 0; m < 4; ++m) _Pragma("unroll") for (int n = 0; n < 2; ++n) _Pragma("unroll") for (int k = 0; k < 2; ++k) \
;         acc[ai][bj][m][n] = __builtin_amdgcn_mfma_f32_16x16x32_bf16(Bt[n][k], At[m][k], acc[ai][bj][m][n], 0, 0, 0); __builtin_amdgcn_s_setprio(0); } while (0)
; #define PG8_WAIT_V(n) asm volatile("s_waitcnt vmcnt(" #n ")" ::: "memory")
; #define PG8_WAIT_L(n) asm volatile("s_waitcnt lgkmcnt(" #n ")" ::: "memory")
; #define PG8_BAR __builtin_amdgcn_s_barrier()
; #define PG8_SCHED __builtin_amdgcn_sched_barrier(0)
; template <class Epi, class Sched, bool ALIGN_EPI = false>
; __device__ __forceinline__ void gemm_phase(PG8_LAS unsigned char* lds, const Gemm g, const Sched& S, const Epi& E, int tid_in) {
;     ...
;             PG8_WAIT_V(8); PG8_WAIT_L(0); PG8_BAR; PG8_MMA(1, 0, At, B0); PG8_MMA(1, 1, At, B1); PG8_BAR; PG8_SCHED;
;             PG8_LDB(B0, 1, 0); PG8_LDB(B1, 1, 1); PG8_SCHED; PG8_LDA(At, 1, 0); PG8_STAGE(PG8_SA(0, 1), a2 + hstepA, voffA);
;             PG8_WAIT_V(8); PG8_WAIT_L(0); PG8_BAR; PG8_MMA(0, 0, At, B0); PG8_MMA(0, 1, At, B1); PG8_BAR; PG8_SCHED;
	s_setprio 1
	s_waitcnt lgkmcnt(0)
	v_mfma_f32_16x16x32_bf16 v[82:85], v[130:133], v[170:173], v[82:85]
	v_mfma_f32_16x16x32_bf16 v[86:89], v[138:141], v[170:173], v[86:89]
	v_mfma_f32_16x16x32_bf16 v[98:101], v[130:133], v[178:181], v[98:101]
	v_mfma_f32_16x16x32_bf16 v[102:105], v[138:141], v[178:181], v[102:105]
	v_mfma_f32_16x16x32_bf16 v[114:117], v[130:133], v[202:205], v[114:117]
	v_mfma_f32_16x16x32_bf16 v[118:121], v[138:141], v[202:205], v[118:121]
	v_mfma_f32_16x16x32_bf16 v[64:67], v[134:137], v[166:169], v[64:67]
	v_mfma_f32_16x16x32_bf16 v[68:71], v[142:145], v[166:169], v[68:71]
	v_mfma_f32_16x16x32_bf16 v[82:85], v[134:137], v[174:177], v[82:85]
	v_mfma_f32_16x16x32_bf16 v[86:89], v[142:145], v[174:177], v[86:89]
	v_mfma_f32_16x16x32_bf16 v[98:101], v[134:137], v[198:201], v[98:101]
	v_mfma_f32_16x16x32_bf16 v[102:105], v[142:145], v[198:201], v[102:105]
	v_mfma_f32_16x16x32_bf16 v[114:117], v[134:137], v[206:209], v[114:117]
	v_mfma_f32_16x16x32_bf16 v[118:121], v[142:145], v[206:209], v[118:121]
	s_setprio 0
	s_setprio 1
	v_mfma_f32_16x16x32_bf16 v[76:79], v[146:149], v[162:165], v[76:79]
	v_mfma_f32_16x16x32_bf16 v[72:75], v[154:157], v[162:165], v[72:75]
	v_mfma_f32_16x16x32_bf16 v[94:97], v[146:149], v[170:173], v[94:97]
	v_mfma_f32_16x16x32_bf16 v[90:93], v[154:157], v[170:173], v[90:93]
	v_mfma_f32_16x16x32_bf16 v[110:113], v[146:149], v[178:181], v[110:113]
	v_mfma_f32_16x16x32_bf16 v[106:109], v[154:157], v[178:181], v[106:109]
	v_mfma_f32_16x16x32_bf16 v[126:129], v[146:149], v[202:205], v[126:129]
	v_mfma_f32_16x16x32_bf16 v[122:125], v[154:157], v[202:205], v[122:125]
	v_mfma_f32_16x16x32_bf16 v[76:79], v[150:153], v[166:169], v[76:79]
	v_mfma_f32_16x16x32_bf16 v[72:75], v[158:161], v[166:169], v[72:75]
	v_mfma_f32_16x16x32_bf16 v[94:97], v[150:153], v[174:177], v[94:97]
	v_mfma_f32_16x16x32_bf16 v[90:93], v[158:161], v[174:177], v[90:93]
	v_mfma_f32_16x16x32_bf16 v[110:113], v[150:153], v[198:201], v[110:113]
	v_mfma_f32_16x16x32_bf16 v[106:109], v[158:161], v[198:201], v[106:109]
	v_mfma_f32_16x16x32_bf16 v[126:129], v[150:153], v[206:209], v[126:129]
	v_mfma_f32_16x16x32_bf16 v[122:125], v[158:161], v[206:209], v[122:125]
	s_setprio 0
	s_barrier
	s_add_i32 s89, 0, 0x18000
	v_add_u32_e32 v80, s89, v245
	s_add_i32 s90, 0, 0x1c000
	ds_read_b128 v[130:133], v80
	ds_read_b128 v[134:137], v80 offset:1024
	ds_read_b128 v[138:141], v80 offset:2048
	ds_read_b128 v[142:145], v80 offset:3072
	v_add_u32_e32 v80, s90, v245
	ds_read_b128 v[146:149], v80
	ds_read_b128 v[150:153], v80 offset:1024
	ds_read_b128 v[154:157], v80 offset:2048
	ds_read_b128 v[158:161], v80 offset:3072
	s_add_u32 s22, s58, s0
	s_addc_u32 s23, s59, 0
	s_mov_b32 m0, s70
	v_lshl_add_u64 v[222:223], s[22:23], 0, v[184:185]
	ds_read_b128 v[162:165], v248 offset:32768
	ds_read_b128 v[166:169], v248 offset:33792
	ds_read_b128 v[170:173], v248 offset:34816
	ds_read_b128 v[174:177], v248 offset:35840
	ds_read_b128 v[178:181], v248 offset:36864
	ds_read_b128 v[198:201], v248 offset:37888
	ds_read_b128 v[202:205], v248 offset:38912
	ds_read_b128 v[206:209], v248 offset:39936
	global_load_lds_dwordx4 v[218:219], off
	s_mov_b32 m0, s71
	s_nop 0
	global_load_lds_dwordx4 v[228:229], off
	s_mov_b32 m0, s72
	s_nop 0
	global_load_lds_dwordx4 v[222:223], off
	v_lshl_add_u64 v[222:223], s[22:23], 0, v[188:189]
	s_mov_b32 m0, s73
	s_nop 0
	global_load_lds_dwordx4 v[222:223], off
	s_waitcnt vmcnt(8)
	s_waitcnt lgkmcnt(0)
	v_mfma_f32_16x16x32_bf16 v[4:7], v[130:133], v[162:165], v[4:7]
	v_mfma_f32_16x16x32_bf16 v[0:3], v[138:141], v[162:165], v[0:3]
	s_barrier
; #define PG8_STAGE(bufoff, gbase, voff) do { _Pragma("unroll") for (int _i = 0; _i < 2; ++_i) \
;         __builtin_amdgcn_global_load_lds((const unsigned*)((const char*)(gbase) + (voff)[_i]), (PG8_LAS unsigned*)(lds + (bufoff) + ldsw + _i * 8192), 16, 0, 0); } while (0)
; #define PG8_LDA(dst, b, h) do { _Pragma("unroll") for (int m = 0; m < 4; ++m) _Pragma("unroll") for (int k = 0; k < 2; ++k) dst[m][k] = *(const PG8_LAS bf16x8*)(lds + PG8_SA(b, h) + aoff + m * 2048 + k * 1024); } while (0)
; #define PG8_MMA(ai, bj, At, Bt) do { __builtin_amdgcn_s_setprio(1); _Pragma("unroll") for (int m = 0; m < 4; ++m) _Pragma("unroll") for (int n = 0; n < 2; ++n) _Pragma("unroll") for (int k = 0; k < 2; ++k) \
;         acc[ai][bj][m][n] = __builtin_amdgcn_mfma_f32_16x16x32_bf16(Bt[n][k], At[m][k], acc[ai][bj][m][n], 0, 0, 0); __builtin_amdgcn_s_setprio(0); } while (0)
; #define PG8_WAIT_V(n) asm volatile("s_waitcnt vmcnt(" #n ")" ::: "memory")
; #define PG8_WAIT_L(n) asm volatile("s_waitcnt lgkmcnt(" #n ")" ::: "memory")
; #define PG8_BAR __builtin_amdgcn_s_barrier()
; #define PG8_SCHED __builtin_amdgcn_sched_barrier(0)
; template <class Epi, class Sched, bool ALIGN_EPI = false>
; __device__ __forceinline__ void gemm_phase(PG8_LAS unsigned char* lds, const Gemm g, const Sched& S, const Epi& E, int tid_in) {
;     ...
;             PG8_WAIT_V(8); PG8_WAIT_L(0); PG8_BAR; PG8_MMA(0, 0, At, B0); PG8_MMA(0, 1, At, B1); PG8_BAR; PG8_SCHED;
;             PG8_LDA(At, 1, 1); PG8_STAGE(PG8_SB(1, 0), b3, voffB); PG8_STAGE(PG8_SB(1, 1), b3 + hstepB, voffB); PG8_STAGE(PG8_SA(1, 0), a3, voffA);
;             PG8_WAIT_V(8); PG8_WAIT_L(0); PG8_BAR; PG8_MMA(1, 0, At, B0); PG8_MMA(1, 1, At, B1); PG8_BAR; PG8_SCHED;
;         }
	s_setprio 1
	s_waitcnt lgkmcnt(0)
	v_mfma_f32_16x16x32_bf16 v[20:23], v[130:133], v[170:173], v[20:23]
	v_mfma_f32_16x16x32_bf16 v[16:19], v[138:141], v[170:173], v[16:19]
	v_mfma_f32_16x16x32_bf16 v[36:39], v[130:133], v[178:181], v[36:39]
	v_mfma_f32_16x16x32_bf16 v[32:35], v[138:141], v[178:181], v[32:35]
	v_mfma_f32_16x16x32_bf16 v[52:55], v[130:133], v[202:205], v[52:55]
	v_mfma_f32_16x16x32_bf16 v[48:51], v[138:141], v[202:205], v[48:51]
	v_mfma_f32_16x16x32_bf16 v[4:7], v[134:137], v[166:169], v[4:7]
	v_mfma_f32_16x16x32_bf16 v[0:3], v[142:145], v[166:169], v[0:3]
	v_mfma_f32_16x16x32_bf16 v[20:23], v[134:137], v[174:177], v[20:23]
	v_mfma_f32_16x16x32_bf16 v[16:19], v[142:145], v[174:177], v[16:19]
	v_mfma_f32_16x16x32_bf16 v[36:39], v[134:137], v[198:201], v[36:39]
	v_mfma_f32_16x16x32_bf16 v[32:35], v[142:145], v[198:201], v[32:35]
	v_mfma_f32_16x16x32_bf16 v[52:55], v[134:137], v[206:209], v[52:55]
	v_mfma_f32_16x16x32_bf16 v[48:51], v[142:145], v[206:209], v[48:51]
	s_setprio 0
	s_setprio 1
	v_mfma_f32_16x16x32_bf16 v[12:15], v[146:149], v[162:165], v[12:15]
	v_mfma_f32_16x16x32_bf16 v[8:11], v[154:157], v[162:165], v[8:11]
	v_mfma_f32_16x16x32_bf16 v[28:31], v[146:149], v[170:173], v[28:31]
	v_mfma_f32_16x16x32_bf16 v[24:27], v[154:157], v[170:173], v[24:27]
	v_mfma_f32_16x16x32_bf16 v[44:47], v[146:149], v[178:181], v[44:47]
	v_mfma_f32_16x16x32_bf16 v[40:43], v[154:157], v[178:181], v[40:43]
	v_mfma_f32_16x16x32_bf16 v[60:63], v[146:149], v[202:205], v[60:63]
	v_mfma_f32_16x16x32_bf16 v[56:59], v[154:157], v[202:205], v[56:59]
	v_mfma_f32_16x16x32_bf16 v[12:15], v[150:153], v[166:169], v[12:15]
	v_mfma_f32_16x16x32_bf16 v[8:11], v[158:161], v[166:169], v[8:11]
	v_mfma_f32_16x16x32_bf16 v[28:31], v[150:153], v[174:177], v[28:31]
	v_mfma_f32_16x16x32_bf16 v[24:27], v[158:161], v[174:177], v[24:27]
	v_mfma_f32_16x16x32_bf16 v[44:47], v[150:153], v[198:201], v[44:47]
	v_mfma_f32_16x16x32_bf16 v[40:43], v[158:161], v[198:201], v[40:43]
	v_mfma_f32_16x16x32_bf16 v[60:63], v[150:153], v[206:209], v[60:63]
	v_mfma_f32_16x16x32_bf16 v[56:59], v[158:161], v[206:209], v[56:59]
	s_setprio 0
	s_barrier
	s_add_i32 s22, s89, s69
	v_lshl_add_u64 v[210:211], v[210:211], 0, s[96:97]
	s_mov_b32 m0, s22
	ds_read_b128 v[162:165], v248 offset:49152
	ds_read_b128 v[166:169], v248 offset:50176
	ds_read_b128 v[170:173], v248 offset:51200
	ds_read_b128 v[174:177], v248 offset:52224
	ds_read_b128 v[178:181], v248 offset:53248
	ds_read_b128 v[198:201], v248 offset:54272
	ds_read_b128 v[202:205], v248 offset:55296
	ds_read_b128 v[206:209], v248 offset:56320
	global_load_lds_dwordx4 v[210:211], off
	v_lshl_add_u64 v[210:211], v[212:213], 0, s[96:97]
	s_add_i32 m0, s22, 0x2000
	s_add_i32 s22, s90, s69
	global_load_lds_dwordx4 v[210:211], off
	v_lshl_add_u64 v[210:211], v[214:215], 0, s[96:97]
	s_mov_b32 m0, s22
	s_nop 0
	global_load_lds_dwordx4 v[210:211], off
	v_lshl_add_u64 v[210:211], v[216:217], 0, s[96:97]
	s_add_i32 m0, s22, 0x2000
	s_nop 0
	global_load_lds_dwordx4 v[210:211], off
	s_waitcnt vmcnt(6)
	s_waitcnt lgkmcnt(0)
	v_mfma_f32_16x16x32_bf16 v[64:67], v[130:133], v[162:165], v[64:67]
	v_mfma_f32_16x16x32_bf16 v[68:71], v[138:141], v[162:165], v[68:71]
	s_barrier
	s_setprio 1
	s_waitcnt lgkmcnt(0)
	v_mfma_f32_16x16x32_bf16 v[82:85], v[130:133], v[170:173], v[82:85]
	v_mfma_f32_16x16x32_bf16 v[86:89], v[138:141], v[170:173], v[86:89]
	v_mfma_f32_16x16x32_bf16 v[98:101], v[130:133], v[178:181], v[98:101]
	v_mfma_f32_16x16x32_bf16 v[102:105], v[138:141], v[178:181], v[102:105]
	v_mfma_f32_16x16x32_bf16 v[114:117], v[130:133], v[202:205], v[114:117]
	v_mfma_f32_16x16x32_bf16 v[118:121], v[138:141], v[202:205], v[118:121]
	v_mfma_f32_16x16x32_bf16 v[64:67], v[134:137], v[166:169], v[64:67]
	v_mfma_f32_16x16x32_bf16 v[68:71], v[142:145], v[166:169], v[68:71]
	v_mfma_f32_16x16x32_bf16 v[82:85], v[134:137], v[174:177], v[82:85]
	v_mfma_f32_16x16x32_bf16 v[86:89], v[142:145], v[174:177], v[86:89]
	v_mfma_f32_16x16x32_bf16 v[98:101], v[134:137], v[198:201], v[98:101]
	v_mfma_f32_16x16x32_bf16 v[102:105], v[142:145], v[198:201], v[102:105]
	v_mfma_f32_16x16x32_bf16 v[114:117], v[134:137], v[206:209], v[114:117]
	v_mfma_f32_16x16x32_bf16 v[118:121], v[142:145], v[206:209], v[118:121]
	s_setprio 0
	s_setprio 1
	v_mfma_f32_16x16x32_bf16 v[76:79], v[146:149], v[162:165], v[76:79]
	v_mfma_f32_16x16x32_bf16 v[72:75], v[154:157], v[162:165], v[72:75]
	v_mfma_f32_16x16x32_bf16 v[94:97], v[146:149], v[170:173], v[94:97]
	v_mfma_f32_16x16x32_bf16 v[90:93], v[154:157], v[170:173], v[90:93]
	v_mfma_f32_16x16x32_bf16 v[110:113], v[146:149], v[178:181], v[110:113]
	v_mfma_f32_16x16x32_bf16 v[106:109], v[154:157], v[178:181], v[106:109]
	v_mfma_f32_16x16x32_bf16 v[126:129], v[146:149], v[202:205], v[126:129]
	v_mfma_f32_16x16x32_bf16 v[122:125], v[154:157], v[202:205], v[122:125]
	v_mfma_f32_16x16x32_bf16 v[76:79], v[150:153], v[166:169], v[76:79]
	v_mfma_f32_16x16x32_bf16 v[72:75], v[158:161], v[166:169], v[72:75]
	v_mfma_f32_16x16x32_bf16 v[94:97], v[150:153], v[174:177], v[94:97]
	v_mfma_f32_16x16x32_bf16 v[90:93], v[158:161], v[174:177], v[90:93]
	v_mfma_f32_16x16x32_bf16 v[110:113], v[150:153], v[198:201], v[110:113]
	v_mfma_f32_16x16x32_bf16 v[106:109], v[158:161], v[198:201], v[106:109]
	v_mfma_f32_16x16x32_bf16 v[126:129], v[150:153], v[206:209], v[126:129]
	v_mfma_f32_16x16x32_bf16 v[122:125], v[158:161], v[206:209], v[122:125]
	s_setprio 0
	s_barrier
	s_add_u32 s60, s60, 0x100
	s_addc_u32 s61, s61, 0
	s_add_u32 s57, s57, 0x100
	s_addc_u32 s62, s62, 0
	s_cmp_ge_u32 s63, s76
	s_mov_b32 s58, s63
	s_cbranch_scc0 .LBB0_267
	s_and_b64 vcc, exec, s[14:15]
	s_cbranch_vccnz .LBB0_271
	s_cmp_lt_i32 s64, 3
	s_mov_b64 s[58:59], -1
	s_cbranch_scc0 .LBB0_272

; __device__ __forceinline__ unsigned cvt_pk_bf16(float lo, float hi) { unsigned r; asm volatile("v_cvt_pk_bf16_f32 %0, %1, %2" : "=v"(r) : "v"(lo), "v"(hi)); return r; }
; #define PG8_ST(v, p) __builtin_nontemporal_store((v), (p))
;     __device__ __forceinline__ float* out() const { return *(const __attribute__((address_space(4))) fptr_t*)(p + 256); }
; __device__ __forceinline__ void epi_res_norm(float* out, bf16_t* xn, const float* gain, float* slots, unsigned* cnt, bool fin, const f32x4 (&acc)[2][2][4][2], const Unit& u, int wr, int wc, int fr, int fq) {
;     ...
;             __builtin_amdgcn_fence(__ATOMIC_ACQUIRE, "agent");
;             asm volatile("s_waitcnt vmcnt(0)" ::: "memory");
;         }
;         asm volatile("s_waitcnt lgkmcnt(0)" ::: "memory"); __builtin_amdgcn_s_barrier(); asm volatile("" ::: "memory");
;         f32x4 gv[4];
; #pragma unroll
;         for (int q = 0; q < 4; ++q) gv[q] = *(const f32x4*)(gain + col0 + (q >> 1) * HALF + (q & 1) * 4);
;         f32x4 pav[8];
; #pragma unroll
;         for (int g = 0; g < 8; ++g) pav[g] = *(const f32x4*)(slots + (size_t)(row0 + (g >> 2) * HALF + (g & 3) * 16) * 16 + 4 * fq);
;         asm volatile("" :: "v"(pav[0]), "v"(pav[1]), "v"(pav[2]), "v"(pav[3]), "v"(pav[4]), "v"(pav[5]), "v"(pav[6]), "v"(pav[7]));
; #pragma unroll
;         for (int g = 0; g < 8; ++g) { const int ai = g >> 2, m = g & 3; const size_t row = (size_t)(row0 + ai * HALF + m * 16);
;             const f32x4 pa = pav[g]; float t = (pa[0] + pa[1]) + (pa[2] + pa[3]);
;             t += __int_as_float(__builtin_amdgcn_ds_swizzle(__float_as_int(t), (16 << 10) | 0x1f));
;             { auto r = __builtin_amdgcn_permlane32_swap(__float_as_uint(t), __float_as_uint(t), false, false); t = __uint_as_float(r[0]) + __uint_as_float(r[1]); }
;             const float rs = __builtin_amdgcn_rsqf(t * (1.0f / 1024.0f) + 1e-6f);
; #pragma unroll
;             for (int bj = 0; bj < 2; ++bj) { const f32x4 o0 = acc[ai][bj][m][0] * rs * gv[2 * bj], o1 = acc[ai][bj][m][1] * rs * gv[2 * bj + 1]; const size_t off = row * 1024 + col0 + bj * HALF;
;                 if (fin) { PG8_ST(o0, (f32x4*)(out + off)); PG8_ST(o1, (f32x4*)(out + off + 4)); }
;                 else { u32x4 w; w.x = cvt_pk_bf16(o0[0], o0[1]); w.y = cvt_pk_bf16(o0[2], o0[3]); w.z = cvt_pk_bf16(o1[0], o1[1]); w.w = cvt_pk_bf16(o1[2], o1[3]); PG8_ST(w, (u32x4*)(xn + off)); } } }
.LBB0_294:
	v_lshlrev_b64 v[130:131], 6, v[174:175]
	s_waitcnt lgkmcnt(0)
	s_barrier
	v_lshl_add_u64 v[130:131], v[192:193], 0, v[130:131]
	v_lshlrev_b64 v[132:133], 6, v[210:211]
	v_lshl_add_u64 v[132:133], v[192:193], 0, v[132:133]
	global_load_dwordx4 v[176:179], v[130:131], off sc1
	global_load_dwordx4 v[170:173], v[132:133], off sc1
	v_lshlrev_b64 v[130:131], 6, v[208:209]
	v_add_u32_e32 v212, 0x80, v174
	v_lshl_add_u64 v[130:131], v[192:193], 0, v[130:131]
	v_lshlrev_b64 v[132:133], 6, v[206:207]
	v_ashrrev_i32_e32 v213, 31, v212
	v_lshl_add_u64 v[132:133], v[192:193], 0, v[132:133]
	global_load_dwordx4 v[166:169], v[130:131], off sc1
	global_load_dwordx4 v[162:165], v[132:133], off sc1
	v_lshlrev_b64 v[130:131], 6, v[212:213]
	v_lshl_add_u64 v[130:131], v[192:193], 0, v[130:131]
	v_lshlrev_b64 v[132:133], 6, v[204:205]
	v_lshl_add_u64 v[132:133], v[192:193], 0, v[132:133]
	global_load_dwordx4 v[158:161], v[130:131], off sc1
	global_load_dwordx4 v[154:157], v[132:133], off sc1
	v_lshlrev_b64 v[130:131], 6, v[202:203]
	v_lshl_add_u64 v[130:131], v[192:193], 0, v[130:131]
	v_lshlrev_b64 v[132:133], 6, v[198:199]
	v_lshl_add_u64 v[132:133], v[192:193], 0, v[132:133]
	global_load_dwordx4 v[150:153], v[130:131], off sc1
	global_load_dwordx4 v[146:149], v[132:133], off sc1
	v_lshl_add_u64 v[134:135], v[200:201], 2, s[2:3]
	global_load_dwordx4 v[142:145], v[134:135], off
	global_load_dwordx4 v[138:141], v[134:135], off offset:16
	global_load_dwordx4 v[130:133], v[134:135], off offset:528
	s_nop 0
	global_load_dwordx4 v[134:137], v[134:135], off offset:512
	v_lshlrev_b64 v[174:175], 10, v[174:175]
	v_lshl_add_u64 v[214:215], v[174:175], 0, v[200:201]
	s_mov_b64 s[58:59], -1
	s_andn2_b64 vcc, exec, s[36:37]
	s_waitcnt vmcnt(0)
	v_mov_b32_e32 v180, v177
	v_mov_b32_e32 v181, v178
	v_mov_b32_e32 v177, v179
	v_pk_add_f32 v[176:177], v[180:181], v[176:177]
	s_nop 0
	v_add_f32_e32 v80, v176, v177
	ds_swizzle_b32 v176, v80 offset:swizzle(SWAP,16)
	s_waitcnt lgkmcnt(0)
	v_add_f32_e32 v80, v80, v176
	v_mov_b32_e32 v176, v80
	s_nop 1
	v_permlane32_swap_b32_e32 v80, v176
	v_add_f32_e32 v80, v80, v176
	v_fmamk_f32 v80, v80, 0x3a800000, v220
	v_rsq_f32_e32 v218, v80
	s_nop 0
	v_pk_mul_f32 v[174:175], v[4:5], v[218:219] op_sel_hi:[1,0]
	v_pk_mul_f32 v[176:177], v[6:7], v[218:219] op_sel_hi:[1,0]
	v_pk_mul_f32 v[216:217], v[0:1], v[218:219] op_sel_hi:[1,0]
	v_pk_mul_f32 v[222:223], v[2:3], v[218:219] op_sel_hi:[1,0]
	v_pk_mul_f32 v[180:181], v[144:145], v[176:177]
	v_pk_mul_f32 v[178:179], v[142:143], v[174:175]
	v_pk_mul_f32 v[176:177], v[140:141], v[222:223]
	v_pk_mul_f32 v[174:175], v[138:139], v[216:217]
	v_lshl_add_u64 v[216:217], v[214:215], 2, s[6:7]
	s_cbranch_vccnz .LBB0_296
	s_mov_b64 s[58:59], 0
	global_store_dwordx4 v[216:217], v[178:181], off
	global_store_dwordx4 v[216:217], v[174:177], off offset:16
